# moved the f32->bf16 conversion of layer 2/3 weights out of phase 0 into the idle workgroups of the previous layer's w_in GEMM round 2 (generic pipelined routine shared by both sites); kv weights still
# baseline (speedup 1.0000x reference)
; __device__ __forceinline__ int bid_fresh() { int t = blockIdx.x; asm volatile("" : "+s"(t)); return t; }
; __device__ __forceinline__ void phase0(PP p, unsigned char* shm) {
;     ...
;     for (int it = bid_fresh(); it < DEPTH * C_LAYER; it += gridDim.x) {
;         const int l = it / C_LAYER; int r = it % C_LAYER;
;         if (r < C_IN) { tconv_tile_w(p->in[5] + (size_t)l * D * INW, INW, r / 14, r % 14, (bf16_t*)(ws + WS_WIN) + (size_t)l * INW * D, D, tile, p->in[4] + (size_t)l * D); continue; } r -= C_IN;
;         if (r < C_OUT) { tconv_tile_w(p->in[23] + (size_t)l * D * D, D, r / 8, r % 8, (bf16_t*)(ws + WS_WOUT) + (size_t)l * D * D, D, tile, p->in[22] + (size_t)l * D); continue; } r -= C_OUT;
;         if (r < C_XQ) { tconv_tile_w(p->in[25] + (size_t)l * D * 512, 512, r / 2, r % 2, (bf16_t*)(ws + WS_WXQ) + (size_t)l * 512 * D, D, tile, p->in[24] + (size_t)l * D); continue; } r -= C_XQ;
;         if (r < C_XQ) { tconv_tile_w(p->in[26] + (size_t)l * D * 512, 512, r / 2, r % 2, (bf16_t*)(ws + WS_WKV) + (size_t)(l * 1024) * D, D, tile); continue; } r -= C_XQ;
;         if (r < C_XQ) { tconv_tile_w(p->in[27] + (size_t)l * D * 512, 512, r / 2, r % 2, (bf16_t*)(ws + WS_WKV) + (size_t)(l * 1024 + 512) * D, D, tile); continue; } r -= C_XQ;
;         if (r < C_XO) { tconv_tile_w(p->in[28] + (size_t)l * 512 * D, D, r / 8, r % 8, (bf16_t*)(ws + WS_WXO) + (size_t)l * D * 512, 512, tile); continue; } r -= C_XO;
;         if (r < C_UP) { tconv_tile_w(p->in[30] + (size_t)l * D * DFF, DFF, r / 32, r % 32, (bf16_t*)(ws + WS_WUP) + (size_t)l * DFF * D, D, tile, p->in[29] + (size_t)l * D); continue; } r -= C_UP;
;         if (r < C_DN) { if (l == 0) tconv_tile_w(p->in[31] + (size_t)l * DFF * D, D, r / 8, r % 8, (bf16_t*)(ws + WS_WDN) + (size_t)l * D * DFF, DFF, tile); continue; } r -= C_DN;
.LBB0_17:
	s_mov_b64 s[14:15], s[0:1]
	s_load_dwordx2 s[12:13], s[14:15], 0x110
	v_writelane_b32 v254, s26, 2
	s_cmpk_gt_i32 s26, 0x2fbf
	s_cbranch_scc1 .LBB0_71
	s_mov_b32 s27, 0
	s_mov_b32 s28, 0
	s_mov_b32 s29, s26
	s_mov_b32 s63, s66
	s_mov_b32 s64, 0
	s_mov_b32 s65, 4
	s_mov_b32 s84, 0x2063ff
	v_writelane_b32 v255, 0, 62

; __device__ __forceinline__ int bid_fresh() { int t = blockIdx.x; asm volatile("" : "+s"(t)); return t; }
; __device__ __forceinline__ void phase0(PP p, unsigned char* shm) {
;     ...
;     for (int it = bid_fresh(); it < DEPTH * C_LAYER; it += gridDim.x) {
;         const int l = it / C_LAYER; int r = it % C_LAYER;
;         if (r < C_IN) { tconv_tile_w(p->in[5] + (size_t)l * D * INW, INW, r / 14, r % 14, (bf16_t*)(ws + WS_WIN) + (size_t)l * INW * D, D, tile, p->in[4] + (size_t)l * D); continue; } r -= C_IN;
;         if (r < C_OUT) { tconv_tile_w(p->in[23] + (size_t)l * D * D, D, r / 8, r % 8, (bf16_t*)(ws + WS_WOUT) + (size_t)l * D * D, D, tile, p->in[22] + (size_t)l * D); continue; } r -= C_OUT;
;         if (r < C_XQ) { tconv_tile_w(p->in[25] + (size_t)l * D * 512, 512, r / 2, r % 2, (bf16_t*)(ws + WS_WXQ) + (size_t)l * 512 * D, D, tile, p->in[24] + (size_t)l * D); continue; } r -= C_XQ;
;         if (r < C_XQ) { tconv_tile_w(p->in[26] + (size_t)l * D * 512, 512, r / 2, r % 2, (bf16_t*)(ws + WS_WKV) + (size_t)(l * 1024) * D, D, tile); continue; } r -= C_XQ;
;         if (r < C_XQ) { tconv_tile_w(p->in[27] + (size_t)l * D * 512, 512, r / 2, r % 2, (bf16_t*)(ws + WS_WKV) + (size_t)(l * 1024 + 512) * D, D, tile); continue; } r -= C_XQ;
;         if (r < C_XO) { tconv_tile_w(p->in[28] + (size_t)l * 512 * D, D, r / 8, r % 8, (bf16_t*)(ws + WS_WXO) + (size_t)l * D * 512, 512, tile); continue; } r -= C_XO;
;         if (r < C_UP) { tconv_tile_w(p->in[30] + (size_t)l * D * DFF, DFF, r / 32, r % 32, (bf16_t*)(ws + WS_WUP) + (size_t)l * DFF * D, D, tile, p->in[29] + (size_t)l * D); continue; } r -= C_UP;
;         if (r < C_DN) { if (l == 0) tconv_tile_w(p->in[31] + (size_t)l * DFF * D, D, r / 8, r % 8, (bf16_t*)(ws + WS_WDN) + (size_t)l * D * DFF, DFF, tile); continue; } r -= C_DN;
;         bf16_t* wsm = (bf16_t*)(ws + WS_WSM) + (size_t)l * 1536 * 512;
;         if (r < C_GLU) { tconv_tile_w(p->in[14] + (size_t)l * 512 * 512, 512, r / 2, r % 2, wsm, 512, tile); continue; } r -= C_GLU;
;         if (r < C_POOL) { const int gi = r >> 2, q = r & 3; tconv_tile(p->in[15] + (size_t)(l * 4 + gi) * 128 * 128, 128, q >> 1, q & 1, wsm + (size_t)(512 + gi * 128) * 512 + gi * 128, 512, tile); continue; } r -= C_POOL;
;         tconv_tile_w(p->in[21] + (size_t)l * 512 * 512, 512, r / 2, r % 2, wsm + (size_t)1024 * 512, 512, tile);
;     }
.Ltc_nextkind_9:
	s_add_u32 s28, s28, 1
	s_mov_b32 s62, 1
	s_cmp_eq_u32 s28, 10
	s_cbranch_scc0 .Ltc_nowrap_6
	s_mov_b32 s28, 0
	s_add_u32 s27, s27, 1
	s_cmp_eq_u32 s27, s65
	s_cbranch_scc1 .Ltc_none_4
.Ltc_nowrap_6:
	s_bfe_u32 s2, s84, 0x30014
	s_cmp_lt_u32 s27, s2
	s_cbranch_scc0 .Ltc_mhi_10
	s_and_b32 s2, s84, 0x3ff
	s_branch .Ltc_mdone_11
.Ltc_mhi_10:
	s_bfe_u32 s2, s84, 0xa000a
.Ltc_mdone_11:
	s_lshr_b32 s2, s2, s28
	s_bitcmp1_b32 s2, 0
	s_cbranch_scc0 .Ltc_nextkind_9
	s_cmp_eq_u32 s28, 9
	s_cbranch_scc0 .Ltc_loadcnt_8
	s_cmp_eq_u32 s27, s64
	s_cbranch_scc0 .Ltc_nextkind_9

; __device__ __forceinline__ int bid_fresh() { int t = blockIdx.x; asm volatile("" : "+s"(t)); return t; }
; __global__ void __launch_bounds__(512, 2) hymba_fwd(Params p_unused) {
;     ...
;           { const int G = (int)gridDim.x, c = (int)bid_fresh(), nfull = 448 % G, nidle = (nfull == 0) ? 0 : G - nfull;
;             if (nidle > 0 && c >= nfull) { for (int r = c - nfull; r < 1024; r += nidle)
;                 tconv_tile_w(p->in[31] + (size_t)l * DFF * D, D, r / 8, r % 8, (bf16_t*)(ws + WS_WDN) + (size_t)l * D * DFF, DFF, (float*)shm); }
;             else if (nidle == 0) { for (int r = c; r < 1024; r += G) tconv_tile_w(p->in[31] + (size_t)l * DFF * D, D, r / 8, r % 8, (bf16_t*)(ws + WS_WDN) + (size_t)l * D * DFF, DFF, (float*)shm); } } }
.LBB0_286:
	s_mov_b32 s12, s30
	v_readlane_b32 s2, v254, 52
	s_cmp_lt_i32 s12, s2
	v_readlane_b32 s16, v254, 49
	s_cselect_b64 s[2:3], -1, 0
	v_readlane_b32 s17, v254, 50
	s_or_b64 s[16:17], s[2:3], s[16:17]
	s_mov_b64 s[2:3], -1
	s_and_b64 vcc, exec, s[16:17]
	s_cbranch_vccnz .LBB0_291
	v_readlane_b32 s2, v254, 52
	s_sub_i32 s2, s12, s2
	s_cmpk_gt_i32 s2, 0x3ff
	v_readlane_b32 s24, v255, 17
	v_readlane_b32 s25, v254, 54
	s_movk_i32 s34, 0x404
	s_cbranch_scc1 .LBB0_290
	v_writelane_b32 v124, s2, 0
	v_writelane_b32 v124, s3, 1
	v_writelane_b32 v124, s4, 2
	v_writelane_b32 v124, s5, 3
	v_writelane_b32 v124, s6, 4
	v_writelane_b32 v124, s7, 5
	v_writelane_b32 v124, s12, 6
	v_writelane_b32 v124, s13, 7
	v_writelane_b32 v124, s14, 8
	v_writelane_b32 v124, s15, 9
	v_writelane_b32 v124, s27, 10
	v_writelane_b32 v124, s28, 11
	v_writelane_b32 v124, s29, 12
	v_writelane_b32 v124, s30, 13
	v_writelane_b32 v124, s31, 14
	v_writelane_b32 v124, s33, 15
	v_writelane_b32 v124, s34, 16
	v_writelane_b32 v124, s35, 17
	v_writelane_b32 v124, s36, 18
	v_writelane_b32 v124, s37, 19
	v_writelane_b32 v124, s38, 20
	v_writelane_b32 v124, s39, 21
	v_writelane_b32 v124, s40, 22
	v_writelane_b32 v124, s41, 23
	v_writelane_b32 v124, s42, 24
	v_writelane_b32 v124, s43, 25
	v_writelane_b32 v124, s44, 26
	v_writelane_b32 v124, s45, 27
	v_writelane_b32 v124, s46, 28
	v_writelane_b32 v124, s47, 29
	v_writelane_b32 v124, s48, 30
	v_writelane_b32 v124, s49, 31
	v_writelane_b32 v124, s50, 32
	v_writelane_b32 v124, s51, 33
	v_writelane_b32 v124, s52, 34
	v_writelane_b32 v124, s53, 35
	v_writelane_b32 v124, s54, 36
	v_writelane_b32 v124, s55, 37
	v_writelane_b32 v124, s56, 38
	v_writelane_b32 v124, s57, 39
	v_writelane_b32 v124, s58, 40
	v_writelane_b32 v124, s59, 41
	v_writelane_b32 v124, s60, 42
	v_writelane_b32 v124, s61, 43
	v_writelane_b32 v124, s62, 44
	v_writelane_b32 v124, s63, 45
	v_writelane_b32 v124, s64, 46
	v_writelane_b32 v124, s65, 47
	v_writelane_b32 v124, s68, 48
	v_writelane_b32 v124, s69, 49
	v_writelane_b32 v124, s70, 50
	v_writelane_b32 v124, s71, 51
	v_writelane_b32 v124, s72, 52
	v_writelane_b32 v124, s73, 53
	v_writelane_b32 v124, s74, 54
	v_writelane_b32 v124, s75, 55
	v_writelane_b32 v124, s76, 56
	v_writelane_b32 v124, s77, 57
	v_writelane_b32 v124, s78, 58
	v_writelane_b32 v124, s79, 59
	v_writelane_b32 v124, s80, 60
	v_writelane_b32 v124, s81, 61
	v_writelane_b32 v124, s82, 62
	v_writelane_b32 v124, s83, 63
	v_writelane_b32 v125, s84, 0
	s_mov_b32 s84, 0xf9c00
	v_readlane_b32 s29, v254, 2
	v_readlane_b32 s3, v254, 52
	v_readlane_b32 s27, v255, 20
	v_readlane_b32 s63, v255, 17
	s_mov_b64 s[14:15], s[0:1]
	s_load_dwordx2 s[12:13], s[0:1], 0x110
	s_nop 3
	s_sub_u32 s29, s29, s3
	s_mov_b32 s28, 9
	s_mov_b32 s64, s27
	s_add_u32 s65, s27, 2
	s_min_u32 s65, s65, 4
	v_writelane_b32 v255, 1, 62
	s_branch .Ltc_entry
.Ltc_ret1:
	v_readlane_b32 s2, v124, 0
	v_readlane_b32 s3, v124, 1
	v_readlane_b32 s4, v124, 2
	v_readlane_b32 s5, v124, 3
	v_readlane_b32 s6, v124, 4
	v_readlane_b32 s7, v124, 5
	v_readlane_b32 s12, v124, 6
	v_readlane_b32 s13, v124, 7
	v_readlane_b32 s14, v124, 8
	v_readlane_b32 s15, v124, 9
	v_readlane_b32 s27, v124, 10
	v_readlane_b32 s28, v124, 11
	v_readlane_b32 s29, v124, 12
	v_readlane_b32 s30, v124, 13
	v_readlane_b32 s31, v124, 14
	v_readlane_b32 s33, v124, 15
	v_readlane_b32 s34, v124, 16
	v_readlane_b32 s35, v124, 17
	v_readlane_b32 s36, v124, 18
	v_readlane_b32 s37, v124, 19
	v_readlane_b32 s38, v124, 20
	v_readlane_b32 s39, v124, 21
	v_readlane_b32 s40, v124, 22
	v_readlane_b32 s41, v124, 23
	v_readlane_b32 s42, v124, 24
	v_readlane_b32 s43, v124, 25
	v_readlane_b32 s44, v124, 26
	v_readlane_b32 s45, v124, 27
	v_readlane_b32 s46, v124, 28
	v_readlane_b32 s47, v124, 29
	v_readlane_b32 s48, v124, 30
	v_readlane_b32 s49, v124, 31
	v_readlane_b32 s50, v124, 32
	v_readlane_b32 s51, v124, 33
	v_readlane_b32 s52, v124, 34
	v_readlane_b32 s53, v124, 35
	v_readlane_b32 s54, v124, 36
	v_readlane_b32 s55, v124, 37
	v_readlane_b32 s56, v124, 38
	v_readlane_b32 s57, v124, 39
	v_readlane_b32 s58, v124, 40
	v_readlane_b32 s59, v124, 41
	v_readlane_b32 s60, v124, 42
	v_readlane_b32 s61, v124, 43
	v_readlane_b32 s62, v124, 44
	v_readlane_b32 s63, v124, 45
	v_readlane_b32 s64, v124, 46
	v_readlane_b32 s65, v124, 47
	v_readlane_b32 s68, v124, 48
	v_readlane_b32 s69, v124, 49
	v_readlane_b32 s70, v124, 50
	v_readlane_b32 s71, v124, 51
	v_readlane_b32 s72, v124, 52
	v_readlane_b32 s73, v124, 53
	v_readlane_b32 s74, v124, 54
	v_readlane_b32 s75, v124, 55
	v_readlane_b32 s76, v124, 56
	v_readlane_b32 s77, v124, 57
	v_readlane_b32 s78, v124, 58
	v_readlane_b32 s79, v124, 59
	v_readlane_b32 s80, v124, 60
	v_readlane_b32 s81, v124, 61
	v_readlane_b32 s82, v124, 62
	v_readlane_b32 s83, v124, 63
	v_readlane_b32 s84, v125, 0
	v_mov_b32_e32 v1, 0
	s_nop 3
